# attention PV: first three V-fragment ds_reads hoisted to the top of the softmax block into free registers (on top of QK burst + wave 0-3 priority)
# baseline (speedup 1.0000x reference)
; #define LAS __attribute__((address_space(3)))
; __device__ __forceinline__ unsigned cvtpk(float lo, float hi) { f32x2_t v = {lo, hi}; bf16x2_t b = __builtin_convertvector(v, bf16x2_t); return __builtin_bit_cast(unsigned, b); }
; __device__ __forceinline__ void unit(const Ctx& C, int xq, int idx, LAS unsigned char* lds) {
;     ...
;         float ls0 = 0.f, ls1 = 0.f;
; #pragma unroll
;         for (int r = 0; r < 16; ++r) {
;             float a_ = __builtin_amdgcn_exp2f(S0[r] - mrun), b_ = __builtin_amdgcn_exp2f(S1[r] - mrun);
;             S0[r] = a_; S1[r] = b_; ls0 += a_; asm("" : "+v"(ls0)); ls1 += b_; asm("" : "+v"(ls1));
;         }
;         lrun += ls0 + ls1;
;         bf16x8 pb[4];
; #pragma unroll
;         for (int mm = 0; mm < 2; ++mm) {
;             u32x4 w0, w1;
;             w0.x = cvtpk(S0[8 * mm + 0], S0[8 * mm + 1]); w0.y = cvtpk(S0[8 * mm + 2], S0[8 * mm + 3]); w0.z = cvtpk(S0[8 * mm + 4], S0[8 * mm + 5]); w0.w = cvtpk(S0[8 * mm + 6], S0[8 * mm + 7]);
;             w1.x = cvtpk(S1[8 * mm + 0], S1[8 * mm + 1]); w1.y = cvtpk(S1[8 * mm + 2], S1[8 * mm + 3]); w1.z = cvtpk(S1[8 * mm + 4], S1[8 * mm + 5]); w1.w = cvtpk(S1[8 * mm + 6], S1[8 * mm + 7]);
;             pb[mm] = __builtin_bit_cast(bf16x8, w0); pb[2 + mm] = __builtin_bit_cast(bf16x8, w1);
;         }
; #pragma unroll
;         for (int kk = 0; kk < 4; ++kk)
; #pragma unroll
;             for (int i = 0; i < 4; ++i) {
;                 const bf16x8 av = *(const LAS bf16x8*)(sb + voff + i * 32 * 144 + kk * 32);
;                 O[i] = __builtin_amdgcn_mfma_f32_32x32x16_bf16(av, pb[kk], O[i], 0, 0, 0);
;             }
.LBB0_522:
	ds_read_b128 v[226:229], v207 offset:18432
	ds_read_b128 v[230:233], v207 offset:18464
	ds_read_b128 v[234:237], v207 offset:23040
	v_sub_f32_e32 v64, v64, v218
	v_exp_f32_e32 v104, v64
	v_sub_f32_e32 v65, v65, v218
	v_sub_f32_e32 v80, v80, v218
	v_exp_f32_e32 v105, v65
	v_exp_f32_e32 v80, v80
	v_sub_f32_e32 v66, v66, v218
	v_sub_f32_e32 v81, v81, v218
	v_exp_f32_e32 v106, v66
	v_sub_f32_e32 v66, v83, v218
	v_add_f32_e32 v96, 0, v104
	v_exp_f32_e32 v81, v81
	v_exp_f32_e32 v83, v66
	v_sub_f32_e32 v66, v67, v218
	v_sub_f32_e32 v82, v82, v218
	v_add_f32_e32 v65, v96, v105
	v_exp_f32_e32 v107, v66
	v_sub_f32_e32 v66, v84, v218
	v_add_f32_e32 v64, 0, v80
	v_exp_f32_e32 v82, v82
	v_exp_f32_e32 v84, v66
	v_sub_f32_e32 v66, v68, v218
	v_add_f32_e32 v65, v106, v65
	v_exp_f32_e32 v108, v66
	v_add_f32_e32 v64, v64, v81
	v_cvt_pk_bf16_f32 v80, v80, v81
	v_add_f32_e32 v65, v107, v65
	v_add_f32_e32 v64, v82, v64
	v_cvt_pk_bf16_f32 v81, v82, v83
	v_add_f32_e32 v68, v108, v65
	v_sub_f32_e32 v65, v85, v218
	v_add_f32_e32 v64, v83, v64
	v_exp_f32_e32 v85, v65
	v_sub_f32_e32 v65, v69, v218
	v_add_f32_e32 v64, v84, v64
	v_exp_f32_e32 v109, v65
	v_add_f32_e32 v69, v85, v64
	v_sub_f32_e32 v64, v86, v218
	v_exp_f32_e32 v110, v64
	v_sub_f32_e32 v86, v87, v218
	v_exp_f32_e32 v111, v86
	v_cvt_pk_bf16_f32 v82, v84, v85
	v_sub_f32_e32 v115, v91, v218
	v_cvt_pk_bf16_f32 v83, v110, v111
	v_sub_f32_e32 v94, v94, v218
	v_exp_f32_e32 v115, v115
	s_waitcnt lgkmcnt(2)
	v_mfma_f32_32x32x16_bf16 v[48:63], v[226:229], v[80:83], v[48:63]
	v_sub_f32_e32 v64, v70, v218
	v_exp_f32_e32 v112, v64
	v_sub_f32_e32 v64, v88, v218
	v_sub_f32_e32 v88, v89, v218
	v_exp_f32_e32 v70, v64
	ds_read_b128 v[64:67], v207 offset:27648
	ds_read_b128 v[100:103], v207 offset:23072
	v_exp_f32_e32 v113, v88
	v_sub_f32_e32 v88, v90, v218
	s_waitcnt lgkmcnt(2)
	v_mfma_f32_32x32x16_bf16 v[32:47], v[234:237], v[80:83], v[32:47]
	v_exp_f32_e32 v114, v88
	ds_read_b128 v[88:91], v207 offset:32256
	ds_read_b128 v[96:99], v207 offset:27680
	v_exp_f32_e32 v94, v94
	v_sub_f32_e32 v71, v71, v218
	v_add_f32_e32 v68, v109, v68
	s_waitcnt lgkmcnt(3)
	v_mfma_f32_32x32x16_bf16 v[16:31], v[64:67], v[80:83], v[16:31]
	v_sub_f32_e32 v64, v92, v218
	v_exp_f32_e32 v92, v64
	v_sub_f32_e32 v64, v93, v218
	v_exp_f32_e32 v93, v64
	v_add_f32_e32 v69, v110, v69
	s_waitcnt lgkmcnt(1)
	v_mfma_f32_32x32x16_bf16 v[0:15], v[88:91], v[80:83], v[0:15]
	v_sub_f32_e32 v80, v95, v218
	v_exp_f32_e32 v95, v80
	v_cvt_pk_bf16_f32 v80, v70, v113
	v_cvt_pk_bf16_f32 v81, v114, v115
	v_cvt_pk_bf16_f32 v82, v92, v93
	v_cvt_pk_bf16_f32 v83, v94, v95
	v_add_f32_e32 v68, v112, v68
	v_add_f32_e32 v69, v111, v69
	v_mfma_f32_32x32x16_bf16 v[48:63], v[230:233], v[80:83], v[48:63]
	v_exp_f32_e32 v84, v71
	v_sub_f32_e32 v71, v72, v218
	ds_read_b128 v[64:67], v207 offset:32288
	v_add_f32_e32 v68, v84, v68
	v_add_f32_e32 v69, v70, v69
	v_mfma_f32_32x32x16_bf16 v[32:47], v[100:103], v[80:83], v[32:47]
	v_exp_f32_e32 v100, v71
	v_sub_f32_e32 v78, v78, v218
	v_add_f32_e32 v72, v100, v68
	v_sub_f32_e32 v68, v73, v218
	v_add_f32_e32 v73, v113, v69
	s_waitcnt lgkmcnt(1)
	v_mfma_f32_32x32x16_bf16 v[16:31], v[96:99], v[80:83], v[16:31]
	v_exp_f32_e32 v96, v68
	ds_read_b128 v[68:71], v207 offset:18496
	s_nop 0
	v_add_f32_e32 v72, v96, v72
	s_waitcnt lgkmcnt(1)
	v_mfma_f32_32x32x16_bf16 v[0:15], v[64:67], v[80:83], v[0:15]
	v_cvt_pk_bf16_f32 v64, v104, v105
	v_cvt_pk_bf16_f32 v65, v106, v107
	v_cvt_pk_bf16_f32 v66, v108, v109
	v_cvt_pk_bf16_f32 v67, v112, v84
	ds_read_b128 v[80:83], v207 offset:23104
	ds_read_b128 v[84:87], v207 offset:18528
	v_add_f32_e32 v98, v114, v73
	s_waitcnt lgkmcnt(2)
	v_mfma_f32_32x32x16_bf16 v[48:63], v[68:71], v[64:67], v[48:63]
	v_sub_f32_e32 v68, v74, v218
	v_exp_f32_e32 v97, v68
	ds_read_b128 v[68:71], v207 offset:27712
	ds_read_b128 v[88:91], v207 offset:23136
	v_add_f32_e32 v98, v115, v98
	v_add_f32_e32 v99, v97, v72
	v_sub_f32_e32 v72, v75, v218
	s_waitcnt lgkmcnt(3)
	v_mfma_f32_32x32x16_bf16 v[32:47], v[80:83], v[64:67], v[32:47]
	v_exp_f32_e32 v101, v72
	ds_read_b128 v[72:75], v207 offset:32320
	ds_read_b128 v[80:83], v207 offset:27744
	s_waitcnt lgkmcnt(3)
	v_mfma_f32_32x32x16_bf16 v[16:31], v[68:71], v[64:67], v[16:31]
	v_sub_f32_e32 v68, v76, v218
	v_exp_f32_e32 v76, v68
	v_sub_f32_e32 v68, v77, v218
	v_exp_f32_e32 v77, v68
	ds_read_b128 v[68:71], v207 offset:32352
	s_waitcnt lgkmcnt(2)
	v_mfma_f32_32x32x16_bf16 v[0:15], v[72:75], v[64:67], v[0:15]
	v_sub_f32_e32 v64, v79, v218
	v_exp_f32_e32 v72, v78
	v_exp_f32_e32 v73, v64
	v_add_f32_e32 v74, v101, v99
	v_cvt_pk_bf16_f32 v64, v100, v96
	v_cvt_pk_bf16_f32 v65, v97, v101
	v_cvt_pk_bf16_f32 v66, v76, v77
	v_cvt_pk_bf16_f32 v67, v72, v73
	v_add_f32_e32 v74, v76, v74
	v_add_f32_e32 v75, v92, v98
	v_mfma_f32_32x32x16_bf16 v[48:63], v[84:87], v[64:67], v[48:63]
	s_nop 0
	v_add_f32_e32 v74, v77, v74
	v_add_f32_e32 v75, v93, v75
	v_mfma_f32_32x32x16_bf16 v[32:47], v[88:91], v[64:67], v[32:47]
	v_add_f32_e32 v72, v72, v74
	v_add_f32_e32 v75, v94, v75
	v_add_f32_e32 v72, v73, v72
	s_waitcnt lgkmcnt(1)
	v_mfma_f32_32x32x16_bf16 v[16:31], v[80:83], v[64:67], v[16:31]
	v_add_f32_e32 v74, v95, v75
	s_nop 0
	v_add_f32_e32 v72, v74, v72
	v_add_f32_e32 v217, v217, v72
	s_waitcnt lgkmcnt(0)
	v_mfma_f32_32x32x16_bf16 v[0:15], v[68:71], v[64:67], v[0:15]

; #define LAS __attribute__((address_space(3)))
; __device__ __forceinline__ unsigned cvtpk(float lo, float hi) { f32x2_t v = {lo, hi}; bf16x2_t b = __builtin_convertvector(v, bf16x2_t); return __builtin_bit_cast(unsigned, b); }
; __device__ __forceinline__ void unit(const Ctx& C, int xq, int idx, LAS unsigned char* lds) {
;     ...
;         float ls0 = 0.f, ls1 = 0.f;
; #pragma unroll
;         for (int r = 0; r < 16; ++r) {
;             float a_ = __builtin_amdgcn_exp2f(S0[r] - mrun), b_ = __builtin_amdgcn_exp2f(S1[r] - mrun);
;             S0[r] = a_; S1[r] = b_; ls0 += a_; asm("" : "+v"(ls0)); ls1 += b_; asm("" : "+v"(ls1));
;         }
;         lrun += ls0 + ls1;
;         bf16x8 pb[4];
; #pragma unroll
;         for (int mm = 0; mm < 2; ++mm) {
;             u32x4 w0, w1;
;             w0.x = cvtpk(S0[8 * mm + 0], S0[8 * mm + 1]); w0.y = cvtpk(S0[8 * mm + 2], S0[8 * mm + 3]); w0.z = cvtpk(S0[8 * mm + 4], S0[8 * mm + 5]); w0.w = cvtpk(S0[8 * mm + 6], S0[8 * mm + 7]);
;             w1.x = cvtpk(S1[8 * mm + 0], S1[8 * mm + 1]); w1.y = cvtpk(S1[8 * mm + 2], S1[8 * mm + 3]); w1.z = cvtpk(S1[8 * mm + 4], S1[8 * mm + 5]); w1.w = cvtpk(S1[8 * mm + 6], S1[8 * mm + 7]);
;             pb[mm] = __builtin_bit_cast(bf16x8, w0); pb[2 + mm] = __builtin_bit_cast(bf16x8, w1);
;         }
; #pragma unroll
;         for (int kk = 0; kk < 4; ++kk)
; #pragma unroll
;             for (int i = 0; i < 4; ++i) {
;                 const bf16x8 av = *(const LAS bf16x8*)(sb + voff + i * 32 * 144 + kk * 32);
;                 O[i] = __builtin_amdgcn_mfma_f32_32x32x16_bf16(av, pb[kk], O[i], 0, 0, 0);
;             }
.LBB0_543:
	ds_read_b128 v[226:229], v207 offset:55296
	ds_read_b128 v[230:233], v207 offset:55328
	ds_read_b128 v[234:237], v207 offset:59904
	v_sub_f32_e32 v64, v64, v218
	v_exp_f32_e32 v104, v64
	v_sub_f32_e32 v65, v65, v218
	v_sub_f32_e32 v80, v80, v218
	v_exp_f32_e32 v105, v65
	v_exp_f32_e32 v80, v80
	v_sub_f32_e32 v66, v66, v218
	v_sub_f32_e32 v81, v81, v218
	v_exp_f32_e32 v106, v66
	v_sub_f32_e32 v66, v83, v218
	v_add_f32_e32 v96, 0, v104
	v_exp_f32_e32 v81, v81
	v_exp_f32_e32 v83, v66
	v_sub_f32_e32 v66, v67, v218
	v_sub_f32_e32 v82, v82, v218
	v_add_f32_e32 v65, v96, v105
	v_exp_f32_e32 v107, v66
	v_sub_f32_e32 v66, v84, v218
	v_add_f32_e32 v64, 0, v80
	v_exp_f32_e32 v82, v82
	v_exp_f32_e32 v84, v66
	v_sub_f32_e32 v66, v68, v218
	v_add_f32_e32 v65, v106, v65
	v_exp_f32_e32 v108, v66
	v_add_f32_e32 v64, v64, v81
	v_cvt_pk_bf16_f32 v80, v80, v81
	v_add_f32_e32 v65, v107, v65
	v_add_f32_e32 v64, v82, v64
	v_cvt_pk_bf16_f32 v81, v82, v83
	v_add_f32_e32 v68, v108, v65
	v_sub_f32_e32 v65, v85, v218
	v_add_f32_e32 v64, v83, v64
	v_exp_f32_e32 v85, v65
	v_sub_f32_e32 v65, v69, v218
	v_add_f32_e32 v64, v84, v64
	v_exp_f32_e32 v109, v65
	v_add_f32_e32 v69, v85, v64
	v_sub_f32_e32 v64, v86, v218
	v_exp_f32_e32 v110, v64
	v_sub_f32_e32 v86, v87, v218
	v_exp_f32_e32 v111, v86
	v_cvt_pk_bf16_f32 v82, v84, v85
	v_sub_f32_e32 v115, v91, v218
	v_cvt_pk_bf16_f32 v83, v110, v111
	v_sub_f32_e32 v94, v94, v218
	v_exp_f32_e32 v115, v115
	s_waitcnt lgkmcnt(2)
	v_mfma_f32_32x32x16_bf16 v[48:63], v[226:229], v[80:83], v[48:63]
	v_sub_f32_e32 v64, v70, v218
	v_exp_f32_e32 v112, v64
	v_sub_f32_e32 v64, v88, v218
	v_sub_f32_e32 v88, v89, v218
	v_exp_f32_e32 v70, v64
	ds_read_b128 v[64:67], v207 offset:64512
	ds_read_b128 v[100:103], v207 offset:59936
	v_exp_f32_e32 v113, v88
	v_sub_f32_e32 v88, v90, v218
	s_waitcnt lgkmcnt(2)
	v_mfma_f32_32x32x16_bf16 v[32:47], v[234:237], v[80:83], v[32:47]
	v_exp_f32_e32 v114, v88
	ds_read_b128 v[88:91], v208 offset:13824
	ds_read_b128 v[96:99], v207 offset:64544
	v_exp_f32_e32 v94, v94
	v_sub_f32_e32 v71, v71, v218
	v_add_f32_e32 v68, v109, v68
	s_waitcnt lgkmcnt(3)
	v_mfma_f32_32x32x16_bf16 v[16:31], v[64:67], v[80:83], v[16:31]
	v_sub_f32_e32 v64, v92, v218
	v_exp_f32_e32 v92, v64
	v_sub_f32_e32 v64, v93, v218
	v_exp_f32_e32 v93, v64
	v_add_f32_e32 v69, v110, v69
	s_waitcnt lgkmcnt(1)
	v_mfma_f32_32x32x16_bf16 v[0:15], v[88:91], v[80:83], v[0:15]
	v_sub_f32_e32 v80, v95, v218
	v_exp_f32_e32 v95, v80
	v_cvt_pk_bf16_f32 v80, v70, v113
	v_cvt_pk_bf16_f32 v81, v114, v115
	v_cvt_pk_bf16_f32 v82, v92, v93
	v_cvt_pk_bf16_f32 v83, v94, v95
	v_add_f32_e32 v68, v112, v68
	v_add_f32_e32 v69, v111, v69
	v_mfma_f32_32x32x16_bf16 v[48:63], v[230:233], v[80:83], v[48:63]
	v_exp_f32_e32 v84, v71
	v_sub_f32_e32 v71, v72, v218
	ds_read_b128 v[64:67], v208 offset:13856
	v_add_f32_e32 v68, v84, v68
	v_add_f32_e32 v69, v70, v69
	v_mfma_f32_32x32x16_bf16 v[32:47], v[100:103], v[80:83], v[32:47]
	v_exp_f32_e32 v100, v71
	v_sub_f32_e32 v78, v78, v218
	v_add_f32_e32 v72, v100, v68
	v_sub_f32_e32 v68, v73, v218
	v_add_f32_e32 v73, v113, v69
	s_waitcnt lgkmcnt(1)
	v_mfma_f32_32x32x16_bf16 v[16:31], v[96:99], v[80:83], v[16:31]
	v_exp_f32_e32 v96, v68
	ds_read_b128 v[68:71], v207 offset:55360
	s_nop 0
	v_add_f32_e32 v72, v96, v72
	s_waitcnt lgkmcnt(1)
	v_mfma_f32_32x32x16_bf16 v[0:15], v[64:67], v[80:83], v[0:15]
	v_cvt_pk_bf16_f32 v64, v104, v105
	v_cvt_pk_bf16_f32 v65, v106, v107
	v_cvt_pk_bf16_f32 v66, v108, v109
	v_cvt_pk_bf16_f32 v67, v112, v84
	ds_read_b128 v[80:83], v207 offset:59968
	ds_read_b128 v[84:87], v207 offset:55392
	v_add_f32_e32 v98, v114, v73
	s_waitcnt lgkmcnt(2)
	v_mfma_f32_32x32x16_bf16 v[48:63], v[68:71], v[64:67], v[48:63]
	v_sub_f32_e32 v68, v74, v218
	v_exp_f32_e32 v97, v68
	ds_read_b128 v[68:71], v207 offset:64576
	ds_read_b128 v[88:91], v207 offset:60000
	v_add_f32_e32 v98, v115, v98
	v_add_f32_e32 v99, v97, v72
	v_sub_f32_e32 v72, v75, v218
	s_waitcnt lgkmcnt(3)
	v_mfma_f32_32x32x16_bf16 v[32:47], v[80:83], v[64:67], v[32:47]
	v_exp_f32_e32 v101, v72
	ds_read_b128 v[72:75], v208 offset:13888
	ds_read_b128 v[80:83], v207 offset:64608
	s_waitcnt lgkmcnt(3)
	v_mfma_f32_32x32x16_bf16 v[16:31], v[68:71], v[64:67], v[16:31]
	v_sub_f32_e32 v68, v76, v218
	v_exp_f32_e32 v76, v68
	v_sub_f32_e32 v68, v77, v218
	v_exp_f32_e32 v77, v68
	ds_read_b128 v[68:71], v208 offset:13920
	s_waitcnt lgkmcnt(2)
	v_mfma_f32_32x32x16_bf16 v[0:15], v[72:75], v[64:67], v[0:15]
	v_sub_f32_e32 v64, v79, v218
	v_exp_f32_e32 v72, v78
	v_exp_f32_e32 v73, v64
	v_add_f32_e32 v74, v101, v99
	v_cvt_pk_bf16_f32 v64, v100, v96
	v_cvt_pk_bf16_f32 v65, v97, v101
	v_cvt_pk_bf16_f32 v66, v76, v77
	v_cvt_pk_bf16_f32 v67, v72, v73
	v_add_f32_e32 v74, v76, v74
	v_add_f32_e32 v75, v92, v98
	v_mfma_f32_32x32x16_bf16 v[48:63], v[84:87], v[64:67], v[48:63]
	s_nop 0
	v_add_f32_e32 v74, v77, v74
	v_add_f32_e32 v75, v93, v75
	v_mfma_f32_32x32x16_bf16 v[32:47], v[88:91], v[64:67], v[32:47]
	v_add_f32_e32 v72, v72, v74
	v_add_f32_e32 v75, v94, v75
	v_add_f32_e32 v72, v73, v72
	s_waitcnt lgkmcnt(1)
	v_mfma_f32_32x32x16_bf16 v[16:31], v[80:83], v[64:67], v[16:31]
	v_add_f32_e32 v74, v95, v75
	s_nop 0
	v_add_f32_e32 v72, v74, v72
	v_add_f32_e32 v217, v217, v72
	s_waitcnt lgkmcnt(0)
	v_mfma_f32_32x32x16_bf16 v[0:15], v[68:71], v[64:67], v[0:15]
	s_add_i32 s34, s92, -2
	s_cmp_ge_u32 s34, s37
	s_cbranch_scc1 .LBB0_535
